# out-proj epilogue residual stores: cache policy nt sc1 instead of nt
# speedup vs baseline: 1.0067x; 1.0001x over previous
.LBB0_57:
	s_cmp_gt_i32 s68, 0
	s_waitcnt vmcnt(6)
	s_cselect_b32 s69, -1, 2
	s_mul_i32 s70, s68, 0x6000
	s_waitcnt lgkmcnt(0)
	s_add_i32 s69, s69, s68
	v_add_u32_e32 v135, s70, v149
	v_add_u32_e32 v0, s70, v148
	s_mulk_i32 s69, 0x6000
	v_add_u32_e32 v164, v135, v152
	s_barrier
	v_lshl_add_u64 v[180:181], v[138:139], 0, s[0:1]
	v_add_u32_e32 v159, s69, v146
	v_lshl_add_u64 v[184:185], v[136:137], 0, s[0:1]
	v_add_u32_e32 v192, s69, v147
	v_add_u32_e32 v176, v0, v152
	ds_read_b128 v[140:143], v176
	ds_read_b128 v[160:163], v164
	ds_read_b128 v[164:167], v164 offset:2048
	v_lshl_add_u64 v[182:183], v[180:181], 0, s[88:89]
	v_lshl_add_u64 v[186:187], v[184:185], 0, s[88:89]
	v_add_u32_e32 v193, 0x4000, v192
	v_lshl_add_u64 v[188:189], v[180:181], 0, s[90:91]
	v_add_u32_e32 v194, 0x400, v159
	v_lshl_add_u64 v[190:191], v[180:181], 0, s[78:79]
	v_add_u32_e32 v195, 0x800, v159
	ds_read_b128 v[168:171], v176 offset:2048
	ds_read_b128 v[172:175], v176 offset:4096
	ds_read_b128 v[176:179], v176 offset:6144
	s_waitcnt lgkmcnt(3)
	s_setprio 1
	v_mfma_f32_32x32x16_bf16 v[114:129], v[140:143], v[160:163], v[114:129]
	v_mfma_f32_32x32x16_bf16 v[98:113], v[140:143], v[164:167], v[98:113]
	v_readfirstlane_b32 s69, v159
	s_mov_b32 m0, s69
	s_nop 0
	global_load_lds_dwordx4 v[182:183], off
	s_waitcnt lgkmcnt(2)
	v_mfma_f32_32x32x16_bf16 v[82:97], v[168:171], v[160:163], v[82:97]
	v_mfma_f32_32x32x16_bf16 v[66:81], v[168:171], v[164:167], v[66:81]
	v_readfirstlane_b32 s69, v194
	s_mov_b32 m0, s69
	s_nop 0
	global_load_lds_dwordx4 v[188:189], off
	s_waitcnt lgkmcnt(1)
	v_mfma_f32_32x32x16_bf16 v[50:65], v[172:175], v[160:163], v[50:65]
	v_mfma_f32_32x32x16_bf16 v[34:49], v[172:175], v[164:167], v[34:49]
	v_readfirstlane_b32 s69, v195
	s_mov_b32 m0, s69
	s_nop 0
	global_load_lds_dwordx4 v[190:191], off
	s_waitcnt lgkmcnt(0)
	v_mfma_f32_32x32x16_bf16 v[18:33], v[176:179], v[160:163], v[18:33]
	v_mfma_f32_32x32x16_bf16 v[2:17], v[176:179], v[164:167], v[2:17]
	s_setprio 0
	v_add_u32_e32 v0, v0, v153
	v_add_u32_e32 v135, v135, v153
	ds_read_b128 v[140:143], v0
	ds_read_b128 v[160:163], v135
	ds_read_b128 v[164:167], v135 offset:2048
	ds_read_b128 v[168:171], v0 offset:2048
	ds_read_b128 v[172:175], v0 offset:4096
	ds_read_b128 v[176:179], v0 offset:6144
	s_waitcnt lgkmcnt(3)
	s_setprio 1
	v_mfma_f32_32x32x16_bf16 v[114:129], v[140:143], v[160:163], v[114:129]
	v_mfma_f32_32x32x16_bf16 v[98:113], v[140:143], v[164:167], v[98:113]
	v_add_u32_e32 v0, 0xc00, v159
	v_lshl_add_u64 v[140:141], v[180:181], 0, s[76:77]
	v_readfirstlane_b32 s69, v0
	s_mov_b32 m0, s69
	s_nop 0
	global_load_lds_dwordx4 v[140:141], off
	s_waitcnt lgkmcnt(2)
	v_mfma_f32_32x32x16_bf16 v[82:97], v[168:171], v[160:163], v[82:97]
	v_mfma_f32_32x32x16_bf16 v[66:81], v[168:171], v[164:167], v[66:81]
	v_readfirstlane_b32 s69, v193
	s_mov_b32 m0, s69
	s_nop 0
	global_load_lds_dwordx4 v[186:187], off
	s_waitcnt lgkmcnt(1)
	v_mfma_f32_32x32x16_bf16 v[50:65], v[172:175], v[160:163], v[50:65]
	v_mfma_f32_32x32x16_bf16 v[34:49], v[172:175], v[164:167], v[34:49]
	v_add_u32_e32 v0, 0x4400, v192
	v_lshl_add_u64 v[140:141], v[184:185], 0, s[90:91]
	v_readfirstlane_b32 s69, v0
	s_mov_b32 m0, s69
	s_nop 0
	global_load_lds_dwordx4 v[140:141], off
	s_waitcnt lgkmcnt(0)
	v_mfma_f32_32x32x16_bf16 v[18:33], v[176:179], v[160:163], v[18:33]
	v_mfma_f32_32x32x16_bf16 v[2:17], v[176:179], v[164:167], v[2:17]
	s_setprio 0
	s_add_i32 s69, s68, 1
	s_cmp_lt_i32 s68, 2
	s_cselect_b32 s68, s69, 0
	s_add_u32 s0, s0, 0x80
	s_addc_u32 s1, s1, 0
	s_cmpk_eq_i32 s0, 0xf00
	s_cbranch_scc0 .LBB0_57
	s_waitcnt vmcnt(6)
	s_mul_i32 s0, s68, 0x6000
	s_waitcnt lgkmcnt(0)
	v_add_u32_e32 v135, s0, v149
	v_add_u32_e32 v0, s0, v148
	v_add_u32_e32 v160, v135, v152
	s_barrier
	v_add_u32_e32 v159, v0, v152
	ds_read_b128 v[136:139], v159
	ds_read_b128 v[140:143], v160
	ds_read_b128 v[160:163], v160 offset:2048
	ds_read_b128 v[164:167], v159 offset:2048
	ds_read_b128 v[168:171], v159 offset:4096
	ds_read_b128 v[172:175], v159 offset:6144
	s_waitcnt lgkmcnt(3)
	s_setprio 1
	v_mfma_f32_32x32x16_bf16 v[114:129], v[136:139], v[140:143], v[114:129]
	v_mfma_f32_32x32x16_bf16 v[98:113], v[136:139], v[160:163], v[98:113]
	s_waitcnt lgkmcnt(2)
	v_mfma_f32_32x32x16_bf16 v[82:97], v[164:167], v[140:143], v[82:97]
	v_mfma_f32_32x32x16_bf16 v[66:81], v[164:167], v[160:163], v[66:81]
	s_waitcnt lgkmcnt(1)
	v_mfma_f32_32x32x16_bf16 v[50:65], v[168:171], v[140:143], v[50:65]
	v_mfma_f32_32x32x16_bf16 v[34:49], v[168:171], v[160:163], v[34:49]
	s_waitcnt lgkmcnt(0)
	v_mfma_f32_32x32x16_bf16 v[18:33], v[172:175], v[140:143], v[18:33]
	v_mfma_f32_32x32x16_bf16 v[2:17], v[172:175], v[160:163], v[2:17]
	s_setprio 0
	v_add_u32_e32 v0, v0, v153
	v_add_u32_e32 v135, v135, v153
	ds_read_b128 v[136:139], v0
	ds_read_b128 v[140:143], v135
	ds_read_b128 v[160:163], v135 offset:2048
	ds_read_b128 v[164:167], v0 offset:2048
	ds_read_b128 v[168:171], v0 offset:4096
	ds_read_b128 v[172:175], v0 offset:6144
	s_waitcnt lgkmcnt(3)
	s_setprio 1
	v_mfma_f32_32x32x16_bf16 v[114:129], v[136:139], v[140:143], v[114:129]
	v_mfma_f32_32x32x16_bf16 v[98:113], v[136:139], v[160:163], v[98:113]
	s_waitcnt lgkmcnt(2)
	v_mfma_f32_32x32x16_bf16 v[82:97], v[164:167], v[140:143], v[82:97]
	v_mfma_f32_32x32x16_bf16 v[66:81], v[164:167], v[160:163], v[66:81]
	s_waitcnt lgkmcnt(1)
	v_mfma_f32_32x32x16_bf16 v[50:65], v[168:171], v[140:143], v[50:65]
	v_mfma_f32_32x32x16_bf16 v[34:49], v[168:171], v[160:163], v[34:49]
	s_waitcnt lgkmcnt(0)
	v_mfma_f32_32x32x16_bf16 v[18:33], v[172:175], v[140:143], v[18:33]
	v_mfma_f32_32x32x16_bf16 v[2:17], v[172:175], v[160:163], v[2:17]
	s_setprio 0
	s_waitcnt vmcnt(0)
	s_waitcnt lgkmcnt(0)
	s_barrier
	ds_read_b128 v[136:139], v154
	ds_read_b128 v[140:143], v155
	ds_read_b128 v[160:163], v155 offset:2048
	ds_read_b128 v[164:167], v154 offset:2048
	ds_read_b128 v[168:171], v154 offset:4096
	ds_read_b128 v[172:175], v154 offset:6144
	s_waitcnt lgkmcnt(3)
	s_setprio 1
	v_mfma_f32_32x32x16_bf16 v[114:129], v[136:139], v[140:143], v[114:129]
	v_mfma_f32_32x32x16_bf16 v[98:113], v[136:139], v[160:163], v[98:113]
	s_waitcnt lgkmcnt(2)
	v_mfma_f32_32x32x16_bf16 v[82:97], v[164:167], v[140:143], v[82:97]
	v_mfma_f32_32x32x16_bf16 v[66:81], v[164:167], v[160:163], v[66:81]
	s_waitcnt lgkmcnt(1)
	v_mfma_f32_32x32x16_bf16 v[50:65], v[168:171], v[140:143], v[50:65]
	v_mfma_f32_32x32x16_bf16 v[34:49], v[168:171], v[160:163], v[34:49]
	s_waitcnt lgkmcnt(0)
	v_mfma_f32_32x32x16_bf16 v[18:33], v[172:175], v[140:143], v[18:33]
	v_mfma_f32_32x32x16_bf16 v[2:17], v[172:175], v[160:163], v[2:17]
	s_setprio 0
	ds_read_b128 v[136:139], v156
	ds_read_b128 v[140:143], v157
	ds_read_b128 v[160:163], v157 offset:2048
	ds_read_b128 v[164:167], v156 offset:2048
	ds_read_b128 v[168:171], v156 offset:4096
	ds_read_b128 v[172:175], v156 offset:6144
	s_waitcnt lgkmcnt(3)
	s_setprio 1
	v_mfma_f32_32x32x16_bf16 v[114:129], v[136:139], v[140:143], v[114:129]
	v_mfma_f32_32x32x16_bf16 v[98:113], v[136:139], v[160:163], v[98:113]
	s_waitcnt lgkmcnt(2)
	v_mfma_f32_32x32x16_bf16 v[82:97], v[164:167], v[140:143], v[82:97]
	v_mfma_f32_32x32x16_bf16 v[66:81], v[164:167], v[160:163], v[66:81]
	s_waitcnt lgkmcnt(1)
	v_mfma_f32_32x32x16_bf16 v[50:65], v[168:171], v[140:143], v[50:65]
	v_mfma_f32_32x32x16_bf16 v[34:49], v[168:171], v[160:163], v[34:49]
	s_waitcnt lgkmcnt(0)
	v_mfma_f32_32x32x16_bf16 v[18:33], v[172:175], v[140:143], v[18:33]
	v_mfma_f32_32x32x16_bf16 v[2:17], v[172:175], v[160:163], v[2:17]
	s_setprio 0
	v_add_u32_e32 v138, s29, v151
	v_or_b32_e32 v136, s31, v150
	v_ashrrev_i32_e32 v139, 31, v138
	v_lshlrev_b64 v[142:143], 10, v[138:139]
	v_ashrrev_i32_e32 v137, 31, v136
	v_lshl_add_u64 v[142:143], v[142:143], 0, v[136:137]
	s_ashr_i32 s0, s28, 4
	v_lshlrev_b64 v[160:161], 2, v[142:143]
	s_add_i32 s0, s0, s10
	v_lshl_add_u64 v[142:143], s[98:99], 0, v[160:161]
	s_movk_i32 s29, 0x2000
	s_mul_hi_i32 s1, s0, 0x3000
	s_mulk_i32 s0, 0x3000
	v_add_co_u32_e32 v162, vcc, s29, v142
	s_add_u32 s0, s4, s0
	s_nop 0
	v_addc_co_u32_e32 v163, vcc, 0, v143, vcc
	s_addc_u32 s1, s5, s1
	v_add_co_u32_e32 v164, vcc, s73, v142
	s_add_u32 s0, s0, 0x2000
	s_nop 0
	v_addc_co_u32_e32 v165, vcc, 0, v143, vcc
	s_addc_u32 s1, s1, 0
	v_add_co_u32_e32 v166, vcc, s75, v142
	v_lshl_add_u64 v[140:141], v[136:137], 2, s[0:1]
	s_nop 0
	v_addc_co_u32_e32 v167, vcc, 0, v143, vcc
	s_waitcnt vmcnt(0) lgkmcnt(0)
	s_barrier
	global_load_dword v0, v[140:141], off
	v_add_co_u32_e32 v168, vcc, s95, v142
	s_mov_b32 s31, 0x11000
	s_nop 0
	v_addc_co_u32_e32 v169, vcc, 0, v143, vcc
	global_load_dword v135, v[142:143], off nt
	global_load_dword v139, v[162:163], off offset:-4096 nt
	global_load_dword v159, v[162:163], off nt
	global_load_dword v188, v[166:167], off offset:-4096 nt
	global_load_dword v189, v[166:167], off nt
	global_load_dword v190, v[168:169], off offset:-4096 nt
	global_load_dword v191, v[168:169], off nt
	global_load_dword v186, v[164:165], off nt
	v_add_co_u32_e32 v170, vcc, s31, v142
	s_mov_b32 s36, 0x13000
	s_nop 0
	v_addc_co_u32_e32 v171, vcc, 0, v143, vcc
	v_add_co_u32_e32 v172, vcc, s36, v142
	s_mov_b32 s37, 0x19000
	s_nop 0
	v_addc_co_u32_e32 v173, vcc, 0, v143, vcc
	global_load_dword v192, v[170:171], off offset:-4096 nt
	global_load_dword v193, v[170:171], off nt
	v_add_co_u32_e32 v174, vcc, s37, v142
	s_mov_b32 s39, 0x1b000
	s_nop 0
	v_addc_co_u32_e32 v175, vcc, 0, v143, vcc
	global_load_dword v194, v[172:173], off offset:-4096 nt
	global_load_dword v195, v[172:173], off nt
	v_add_co_u32_e32 v176, vcc, s39, v142
	global_load_dword v196, v[174:175], off offset:-4096 nt
	global_load_dword v197, v[174:175], off nt
	v_addc_co_u32_e32 v177, vcc, 0, v143, vcc
	global_load_dword v198, v[176:177], off offset:-4096 nt
	global_load_dword v199, v[176:177], off nt
	s_movk_i32 s28, 0x1000
	v_add_co_u32_e32 v178, vcc, s28, v142
	v_lshl_add_u64 v[160:161], s[56:57], 0, v[160:161]
	s_nop 0
	v_addc_co_u32_e32 v179, vcc, 0, v143, vcc
	v_add_co_u32_e32 v180, vcc, s94, v142
	s_mov_b32 s38, 0x1a000
	s_nop 0
	v_addc_co_u32_e32 v181, vcc, 0, v143, vcc
	v_add_co_u32_e32 v182, vcc, s87, v142
	s_add_i32 s34, s34, s30
	s_nop 0
	v_addc_co_u32_e32 v183, vcc, 0, v143, vcc
	v_add_co_u32_e32 v184, vcc, s29, v160
	s_cmp_ge_i32 s34, s35
	s_nop 0
	v_addc_co_u32_e32 v185, vcc, 0, v161, vcc
	s_waitcnt vmcnt(15)
	v_fmac_f32_e32 v135, v114, v0
	s_waitcnt vmcnt(13)
	v_fmac_f32_e32 v159, v116, v0
	v_add_co_u32_e32 v116, vcc, s73, v160
	v_fmac_f32_e32 v139, v115, v0
	global_store_dword v[160:161], v135, off nt sc1
	global_store_dword v[184:185], v139, off offset:-4096 nt sc1
	s_waitcnt vmcnt(10)
	v_fmac_f32_e32 v186, v117, v0
	v_addc_co_u32_e32 v117, vcc, 0, v161, vcc
	global_store_dword v[116:117], v186, off nt sc1
	v_add_co_u32_e32 v186, vcc, s75, v160
	v_fmac_f32_e32 v188, v118, v0
	s_nop 0
	v_addc_co_u32_e32 v187, vcc, 0, v161, vcc
	v_add_co_u32_e32 v118, vcc, s95, v160
	v_fmac_f32_e32 v189, v119, v0
	s_nop 0
	v_addc_co_u32_e32 v119, vcc, 0, v161, vcc
	v_fmac_f32_e32 v190, v120, v0
	v_add_co_u32_e32 v120, vcc, s31, v160
	v_fmac_f32_e32 v191, v121, v0
	s_nop 0
	v_addc_co_u32_e32 v121, vcc, 0, v161, vcc
	s_waitcnt vmcnt(10)
	v_fmac_f32_e32 v192, v122, v0
	v_add_co_u32_e32 v122, vcc, s36, v160
	s_waitcnt vmcnt(9)
	v_fmac_f32_e32 v193, v123, v0
	v_addc_co_u32_e32 v123, vcc, 0, v161, vcc
	s_waitcnt vmcnt(8)
	v_fmac_f32_e32 v194, v124, v0
	v_add_co_u32_e32 v124, vcc, s37, v160
	s_waitcnt vmcnt(7)
	v_fmac_f32_e32 v195, v125, v0
	v_addc_co_u32_e32 v125, vcc, 0, v161, vcc
	v_or_b32_e32 v114, 32, v136
	s_waitcnt vmcnt(6)
	v_fmac_f32_e32 v196, v126, v0
	v_add_co_u32_e32 v126, vcc, s39, v160
	v_ashrrev_i32_e32 v115, 31, v114
	s_waitcnt vmcnt(5)
	v_fmac_f32_e32 v197, v127, v0
	s_waitcnt vmcnt(4)
	v_fmac_f32_e32 v198, v128, v0
	v_addc_co_u32_e32 v127, vcc, 0, v161, vcc
	s_waitcnt vmcnt(3)
	v_fmac_f32_e32 v199, v129, v0
	v_lshl_add_u64 v[114:115], v[114:115], 2, s[0:1]
	s_mov_b32 s0, 0x10000
	global_store_dword v[184:185], v159, off nt sc1
	global_store_dword v[186:187], v188, off offset:-4096 nt sc1
	global_store_dword v[186:187], v189, off nt sc1
	global_store_dword v[118:119], v190, off offset:-4096 nt sc1
	global_store_dword v[118:119], v191, off nt sc1
	global_store_dword v[120:121], v192, off offset:-4096 nt sc1
	global_store_dword v[120:121], v193, off nt sc1
	global_store_dword v[122:123], v194, off offset:-4096 nt sc1
	global_store_dword v[122:123], v195, off nt sc1
	global_store_dword v[124:125], v196, off offset:-4096 nt sc1
	global_store_dword v[124:125], v197, off nt sc1
	global_store_dword v[126:127], v198, off offset:-4096 nt sc1
	global_store_dword v[126:127], v199, off nt sc1
	v_add_co_u32_e32 v128, vcc, s0, v142
	global_load_dword v0, v[114:115], off
	global_load_dword v135, v[142:143], off offset:128 nt
	global_load_dword v139, v[178:179], off offset:128 nt
	v_addc_co_u32_e32 v129, vcc, 0, v143, vcc
	global_load_dword v159, v[162:163], off offset:128 nt
	global_load_dword v178, v[164:165], off offset:128 nt
	global_load_dword v179, v[180:181], off offset:128 nt
	s_nop 0
	global_load_dword v180, v[166:167], off offset:128 nt
	v_add_co_u32_e32 v162, vcc, s72, v142
	s_mov_b32 s1, 0x18000
	s_nop 0
	v_addc_co_u32_e32 v163, vcc, 0, v143, vcc
	global_load_dword v181, v[182:183], off offset:128 nt
	s_nop 0
	global_load_dword v182, v[128:129], off offset:128 nt
	global_load_dword v183, v[168:169], off offset:128 nt
	global_load_dword v188, v[170:171], off offset:128 nt
	v_add_co_u32_e32 v128, vcc, s1, v142
	s_waitcnt vmcnt(9)
	v_fmac_f32_e32 v135, v98, v0
	v_addc_co_u32_e32 v129, vcc, 0, v143, vcc
	global_load_dword v189, v[162:163], off offset:128 nt
	global_load_dword v190, v[128:129], off offset:128 nt
	s_nop 0
	global_load_dword v172, v[172:173], off offset:128 nt
	s_nop 0
	global_load_dword v173, v[174:175], off offset:128 nt
	v_add_co_u32_e32 v128, vcc, s38, v142
	v_or_b32_e32 v98, 32, v138
	s_nop 0
	v_addc_co_u32_e32 v129, vcc, 0, v143, vcc
	global_load_dword v174, v[128:129], off offset:128 nt
	global_load_dword v175, v[176:177], off offset:128 nt
	v_add_co_u32_e32 v128, vcc, s28, v160
	s_waitcnt vmcnt(14)
	v_fmac_f32_e32 v139, v99, v0
	v_addc_co_u32_e32 v129, vcc, 0, v161, vcc
	v_add_co_u32_e32 v142, vcc, s94, v160
	v_ashrrev_i32_e32 v99, 31, v98
	s_nop 0
	v_addc_co_u32_e32 v143, vcc, 0, v161, vcc
	v_add_co_u32_e32 v162, vcc, s87, v160
	v_lshlrev_b64 v[98:99], 10, v[98:99]
	s_nop 0
	v_addc_co_u32_e32 v163, vcc, 0, v161, vcc
	v_add_co_u32_e32 v164, vcc, s0, v160
	v_lshl_add_u64 v[98:99], v[98:99], 0, v[136:137]
	s_nop 0
	v_addc_co_u32_e32 v165, vcc, 0, v161, vcc
	v_add_co_u32_e32 v166, vcc, s72, v160
	v_lshlrev_b64 v[98:99], 2, v[98:99]
	s_nop 0
	v_addc_co_u32_e32 v167, vcc, 0, v161, vcc
	v_add_co_u32_e32 v168, vcc, s1, v160
	s_waitcnt vmcnt(13)
	v_fmac_f32_e32 v159, v100, v0
	v_addc_co_u32_e32 v169, vcc, 0, v161, vcc
	v_add_co_u32_e32 v170, vcc, s38, v160
	s_waitcnt vmcnt(12)
	v_fmac_f32_e32 v178, v101, v0
	v_addc_co_u32_e32 v171, vcc, 0, v161, vcc
	v_lshl_add_u64 v[100:101], s[98:99], 0, v[98:99]
	s_waitcnt vmcnt(11)
	v_fmac_f32_e32 v179, v102, v0
	v_add_co_u32_e32 v102, vcc, s29, v100
	s_waitcnt vmcnt(10)
	v_fmac_f32_e32 v180, v103, v0
	v_addc_co_u32_e32 v103, vcc, 0, v101, vcc
	s_waitcnt vmcnt(9)
	v_fmac_f32_e32 v181, v104, v0
	s_waitcnt vmcnt(7)
	v_fmac_f32_e32 v183, v105, v0
	v_fmac_f32_e32 v182, v106, v0
	s_waitcnt vmcnt(6)
	v_fmac_f32_e32 v188, v107, v0
	v_add_co_u32_e32 v104, vcc, s73, v100
	global_store_dword v[160:161], v135, off offset:128 nt sc1
	global_store_dword v[128:129], v139, off offset:128 nt sc1
	global_store_dword v[184:185], v159, off offset:128 nt sc1
	global_store_dword v[116:117], v178, off offset:128 nt sc1
	global_store_dword v[142:143], v179, off offset:128 nt sc1
	global_store_dword v[186:187], v180, off offset:128 nt sc1
	global_store_dword v[162:163], v181, off offset:128 nt sc1
	global_store_dword v[118:119], v183, off offset:128 nt sc1
	global_store_dword v[164:165], v182, off offset:128 nt sc1
	global_store_dword v[120:121], v188, off offset:128 nt sc1
	v_addc_co_u32_e32 v105, vcc, 0, v101, vcc
	v_add_co_u32_e32 v106, vcc, s75, v100
	v_lshl_add_u64 v[98:99], s[56:57], 0, v[98:99]
	s_nop 0
	v_addc_co_u32_e32 v107, vcc, 0, v101, vcc
	s_waitcnt vmcnt(15)
	v_fmac_f32_e32 v189, v108, v0
	s_waitcnt vmcnt(14)
	v_fmac_f32_e32 v190, v110, v0
	s_waitcnt vmcnt(13)
	v_fmac_f32_e32 v172, v109, v0
	s_waitcnt vmcnt(12)
	v_fmac_f32_e32 v173, v111, v0
	global_store_dword v[166:167], v189, off offset:128 nt sc1
	global_store_dword v[122:123], v172, off offset:128 nt sc1
	global_store_dword v[168:169], v190, off offset:128 nt sc1
	global_store_dword v[124:125], v173, off offset:128 nt sc1
	s_waitcnt vmcnt(15)
	v_fmac_f32_e32 v174, v112, v0
	s_waitcnt vmcnt(14)
	v_fmac_f32_e32 v175, v113, v0
	global_store_dword v[170:171], v174, off offset:128 nt sc1
	global_store_dword v[126:127], v175, off offset:128 nt sc1
	global_load_dword v0, v[140:141], off
	s_nop 0
	global_load_dword v126, v[100:101], off nt
	global_load_dword v127, v[102:103], off offset:-4096 nt
	v_add_co_u32_e32 v108, vcc, s95, v100
	s_waitcnt vmcnt(1)
	v_fmac_f32_e32 v126, v82, v0
	v_addc_co_u32_e32 v109, vcc, 0, v101, vcc
	global_load_dword v128, v[102:103], off nt
	global_load_dword v129, v[106:107], off offset:-4096 nt
	global_load_dword v135, v[106:107], off nt
	global_load_dword v139, v[108:109], off offset:-4096 nt
	global_load_dword v142, v[108:109], off nt
	global_load_dword v143, v[104:105], off nt
	v_add_co_u32_e32 v110, vcc, s31, v100
	s_waitcnt vmcnt(6)
	v_fmac_f32_e32 v127, v83, v0
	v_addc_co_u32_e32 v111, vcc, 0, v101, vcc
	v_add_co_u32_e32 v112, vcc, s36, v100
	global_load_dword v159, v[110:111], off offset:-4096 nt
	global_load_dword v160, v[110:111], off nt
	v_addc_co_u32_e32 v113, vcc, 0, v101, vcc
	v_add_co_u32_e32 v116, vcc, s37, v100
	global_load_dword v161, v[112:113], off offset:-4096 nt
	global_load_dword v162, v[112:113], off nt
	v_addc_co_u32_e32 v117, vcc, 0, v101, vcc
	v_add_co_u32_e32 v118, vcc, s39, v100
	global_load_dword v163, v[116:117], off offset:-4096 nt
	global_load_dword v164, v[116:117], off nt
	v_addc_co_u32_e32 v119, vcc, 0, v101, vcc
	global_load_dword v165, v[118:119], off offset:-4096 nt
	global_load_dword v166, v[118:119], off nt
	v_add_co_u32_e32 v120, vcc, s28, v100
	global_store_dword v[98:99], v126, off nt sc1
	s_nop 0
	v_addc_co_u32_e32 v121, vcc, 0, v101, vcc
	v_add_co_u32_e32 v122, vcc, s94, v100
	s_waitcnt vmcnt(14)
	v_fmac_f32_e32 v128, v84, v0
	v_addc_co_u32_e32 v123, vcc, 0, v101, vcc
	v_add_co_u32_e32 v124, vcc, s87, v100
	s_waitcnt vmcnt(9)
	v_fmac_f32_e32 v143, v85, v0
	v_addc_co_u32_e32 v125, vcc, 0, v101, vcc
	v_add_co_u32_e32 v82, vcc, s29, v98
	v_fmac_f32_e32 v129, v86, v0
	s_nop 0
	v_addc_co_u32_e32 v83, vcc, 0, v99, vcc
	v_add_co_u32_e32 v84, vcc, s73, v98
	global_store_dword v[82:83], v127, off offset:-4096 nt sc1
	s_nop 0
	v_addc_co_u32_e32 v85, vcc, 0, v99, vcc
	v_add_co_u32_e32 v126, vcc, s75, v98
	v_fmac_f32_e32 v135, v87, v0
	s_nop 0
	v_addc_co_u32_e32 v127, vcc, 0, v99, vcc
	v_add_co_u32_e32 v86, vcc, s95, v98
	v_fmac_f32_e32 v139, v88, v0
	s_nop 0
	v_addc_co_u32_e32 v87, vcc, 0, v99, vcc
	v_add_co_u32_e32 v88, vcc, s31, v98
	v_fmac_f32_e32 v142, v89, v0
	s_nop 0
	v_addc_co_u32_e32 v89, vcc, 0, v99, vcc
	s_waitcnt vmcnt(9)
	v_fmac_f32_e32 v159, v90, v0
	v_add_co_u32_e32 v90, vcc, s36, v98
	s_waitcnt vmcnt(8)
	v_fmac_f32_e32 v160, v91, v0
	v_addc_co_u32_e32 v91, vcc, 0, v99, vcc
	s_waitcnt vmcnt(7)
	v_fmac_f32_e32 v161, v92, v0
	v_add_co_u32_e32 v92, vcc, s37, v98
	s_waitcnt vmcnt(6)
	v_fmac_f32_e32 v162, v93, v0
	v_addc_co_u32_e32 v93, vcc, 0, v99, vcc
	s_waitcnt vmcnt(5)
	v_fmac_f32_e32 v163, v94, v0
	v_add_co_u32_e32 v94, vcc, s39, v98
	s_waitcnt vmcnt(4)
	v_fmac_f32_e32 v164, v95, v0
	s_waitcnt vmcnt(3)
	v_fmac_f32_e32 v165, v96, v0
	v_addc_co_u32_e32 v95, vcc, 0, v99, vcc
	s_waitcnt vmcnt(2)
	v_fmac_f32_e32 v166, v97, v0
	global_store_dword v[82:83], v128, off nt sc1
	global_store_dword v[84:85], v143, off nt sc1
	global_store_dword v[126:127], v129, off offset:-4096 nt sc1
	global_store_dword v[126:127], v135, off nt sc1
	global_store_dword v[86:87], v139, off offset:-4096 nt sc1
	global_store_dword v[86:87], v142, off nt sc1
	global_store_dword v[88:89], v159, off offset:-4096 nt sc1
	global_store_dword v[88:89], v160, off nt sc1
	global_store_dword v[90:91], v161, off offset:-4096 nt sc1
	global_store_dword v[90:91], v162, off nt sc1
	global_store_dword v[92:93], v163, off offset:-4096 nt sc1
	global_store_dword v[92:93], v164, off nt sc1
	global_store_dword v[94:95], v165, off offset:-4096 nt sc1
	global_store_dword v[94:95], v166, off nt sc1
	global_load_dword v0, v[114:115], off
	global_load_dword v128, v[100:101], off offset:128 nt
	v_add_co_u32_e32 v96, vcc, s0, v100
	global_load_dword v120, v[120:121], off offset:128 nt
	s_nop 0
	global_load_dword v121, v[102:103], off offset:128 nt
	global_load_dword v129, v[104:105], off offset:128 nt
	s_nop 0
	global_load_dword v122, v[122:123], off offset:128 nt
	v_addc_co_u32_e32 v97, vcc, 0, v101, vcc
	v_add_co_u32_e32 v102, vcc, s72, v100
	global_load_dword v123, v[106:107], off offset:128 nt
	global_load_dword v135, v[108:109], off offset:128 nt
	s_nop 0
	global_load_dword v124, v[124:125], off offset:128 nt
	s_nop 0
	global_load_dword v125, v[96:97], off offset:128 nt
	v_addc_co_u32_e32 v103, vcc, 0, v101, vcc
	v_add_co_u32_e32 v96, vcc, s1, v100
	s_waitcnt vmcnt(8)
	v_fmac_f32_e32 v128, v66, v0
	v_addc_co_u32_e32 v97, vcc, 0, v101, vcc
	global_load_dword v139, v[110:111], off offset:128 nt
	s_nop 0
	global_load_dword v112, v[112:113], off offset:128 nt
	s_nop 0
	global_load_dword v113, v[102:103], off offset:128 nt
	global_load_dword v142, v[96:97], off offset:128 nt
	v_add_co_u32_e32 v96, vcc, s38, v100
	v_or_b32_e32 v66, 64, v138
	s_nop 0
	v_addc_co_u32_e32 v97, vcc, 0, v101, vcc
	global_load_dword v116, v[116:117], off offset:128 nt
	s_nop 0
	global_load_dword v117, v[118:119], off offset:128 nt
	s_nop 0
	global_load_dword v118, v[96:97], off offset:128 nt
	v_add_co_u32_e32 v96, vcc, s28, v98
	s_waitcnt vmcnt(14)
	v_fmac_f32_e32 v120, v67, v0
	v_addc_co_u32_e32 v97, vcc, 0, v99, vcc
	v_add_co_u32_e32 v100, vcc, s94, v98
	v_ashrrev_i32_e32 v67, 31, v66
	s_nop 0
	v_addc_co_u32_e32 v101, vcc, 0, v99, vcc
	v_add_co_u32_e32 v102, vcc, s87, v98
	v_lshlrev_b64 v[66:67], 10, v[66:67]
	s_nop 0
	v_addc_co_u32_e32 v103, vcc, 0, v99, vcc
	v_add_co_u32_e32 v104, vcc, s0, v98
	v_lshl_add_u64 v[66:67], v[66:67], 0, v[136:137]
	s_nop 0
	v_addc_co_u32_e32 v105, vcc, 0, v99, vcc
	v_add_co_u32_e32 v106, vcc, s72, v98
	v_lshlrev_b64 v[66:67], 2, v[66:67]
	s_nop 0
	v_addc_co_u32_e32 v107, vcc, 0, v99, vcc
	v_add_co_u32_e32 v108, vcc, s1, v98
	s_waitcnt vmcnt(13)
	v_fmac_f32_e32 v121, v68, v0
	v_addc_co_u32_e32 v109, vcc, 0, v99, vcc
	v_add_co_u32_e32 v110, vcc, s38, v98
	s_waitcnt vmcnt(12)
	v_fmac_f32_e32 v129, v69, v0
	v_addc_co_u32_e32 v111, vcc, 0, v99, vcc
	v_lshl_add_u64 v[68:69], s[98:99], 0, v[66:67]
	s_waitcnt vmcnt(11)
	v_fmac_f32_e32 v122, v70, v0
	v_add_co_u32_e32 v70, vcc, s29, v68
	s_waitcnt vmcnt(10)
	v_fmac_f32_e32 v123, v71, v0
	v_addc_co_u32_e32 v71, vcc, 0, v69, vcc
	s_waitcnt vmcnt(8)
	v_fmac_f32_e32 v124, v72, v0
	v_fmac_f32_e32 v135, v73, v0
	s_waitcnt vmcnt(7)
	v_fmac_f32_e32 v125, v74, v0
	v_add_co_u32_e32 v72, vcc, s73, v68
	global_store_dword v[98:99], v128, off offset:128 nt sc1
	global_store_dword v[96:97], v120, off offset:128 nt sc1
	global_store_dword v[82:83], v121, off offset:128 nt sc1
	global_store_dword v[84:85], v129, off offset:128 nt sc1
	global_store_dword v[100:101], v122, off offset:128 nt sc1
	global_store_dword v[126:127], v123, off offset:128 nt sc1
	global_store_dword v[102:103], v124, off offset:128 nt sc1
	global_store_dword v[86:87], v135, off offset:128 nt sc1
	global_store_dword v[104:105], v125, off offset:128 nt sc1
	v_addc_co_u32_e32 v73, vcc, 0, v69, vcc
	v_add_co_u32_e32 v74, vcc, s75, v68
	v_lshl_add_u64 v[66:67], s[56:57], 0, v[66:67]
	s_waitcnt vmcnt(15)
	v_fmac_f32_e32 v139, v75, v0
	s_waitcnt vmcnt(14)
	v_fmac_f32_e32 v112, v77, v0
	s_waitcnt vmcnt(13)
	v_fmac_f32_e32 v113, v76, v0
	s_waitcnt vmcnt(12)
	v_fmac_f32_e32 v142, v78, v0
	global_store_dword v[88:89], v139, off offset:128 nt sc1
	global_store_dword v[106:107], v113, off offset:128 nt sc1
	global_store_dword v[90:91], v112, off offset:128 nt sc1
	s_waitcnt vmcnt(14)
	v_fmac_f32_e32 v116, v79, v0
	s_waitcnt vmcnt(13)
	v_fmac_f32_e32 v117, v81, v0
	s_waitcnt vmcnt(12)
	v_fmac_f32_e32 v118, v80, v0
	global_store_dword v[108:109], v142, off offset:128 nt sc1
	global_store_dword v[92:93], v116, off offset:128 nt sc1
	global_store_dword v[110:111], v118, off offset:128 nt sc1
	global_store_dword v[94:95], v117, off offset:128 nt sc1
	global_load_dword v0, v[140:141], off
	s_nop 0
	global_load_dword v92, v[68:69], off nt
	global_load_dword v93, v[70:71], off offset:-4096 nt
	v_addc_co_u32_e32 v75, vcc, 0, v69, vcc
	v_add_co_u32_e32 v76, vcc, s95, v68
	s_waitcnt vmcnt(1)
	v_fmac_f32_e32 v92, v50, v0
	v_addc_co_u32_e32 v77, vcc, 0, v69, vcc
	global_load_dword v94, v[70:71], off nt
	global_load_dword v95, v[74:75], off offset:-4096 nt
	global_load_dword v96, v[74:75], off nt
	global_load_dword v97, v[76:77], off offset:-4096 nt
	global_load_dword v98, v[76:77], off nt
	global_load_dword v99, v[72:73], off nt
	v_add_co_u32_e32 v78, vcc, s31, v68
	s_waitcnt vmcnt(6)
	v_fmac_f32_e32 v93, v51, v0
	v_addc_co_u32_e32 v79, vcc, 0, v69, vcc
	v_add_co_u32_e32 v80, vcc, s36, v68
	global_load_dword v100, v[78:79], off offset:-4096 nt
	global_load_dword v101, v[78:79], off nt
	v_addc_co_u32_e32 v81, vcc, 0, v69, vcc
	v_add_co_u32_e32 v82, vcc, s37, v68
	global_load_dword v102, v[80:81], off offset:-4096 nt
	global_load_dword v103, v[80:81], off nt
	v_addc_co_u32_e32 v83, vcc, 0, v69, vcc
	v_add_co_u32_e32 v84, vcc, s39, v68
	global_load_dword v104, v[82:83], off offset:-4096 nt
	global_load_dword v105, v[82:83], off nt
	v_addc_co_u32_e32 v85, vcc, 0, v69, vcc
	global_load_dword v106, v[84:85], off offset:-4096 nt
	global_load_dword v107, v[84:85], off nt
	v_add_co_u32_e32 v86, vcc, s28, v68
	global_store_dword v[66:67], v92, off nt sc1
	s_nop 0
	v_addc_co_u32_e32 v87, vcc, 0, v69, vcc
	v_add_co_u32_e32 v88, vcc, s94, v68
	s_waitcnt vmcnt(14)
	v_fmac_f32_e32 v94, v52, v0
	v_addc_co_u32_e32 v89, vcc, 0, v69, vcc
	v_add_co_u32_e32 v90, vcc, s87, v68
	s_waitcnt vmcnt(9)
	v_fmac_f32_e32 v99, v53, v0
	v_addc_co_u32_e32 v91, vcc, 0, v69, vcc
	v_add_co_u32_e32 v50, vcc, s29, v66
	v_fmac_f32_e32 v95, v54, v0
	s_nop 0
	v_addc_co_u32_e32 v51, vcc, 0, v67, vcc
	v_add_co_u32_e32 v52, vcc, s73, v66
	global_store_dword v[50:51], v93, off offset:-4096 nt sc1
	s_nop 0
	v_addc_co_u32_e32 v53, vcc, 0, v67, vcc
	v_add_co_u32_e32 v92, vcc, s75, v66
	v_fmac_f32_e32 v96, v55, v0
	s_nop 0
	v_addc_co_u32_e32 v93, vcc, 0, v67, vcc
	v_add_co_u32_e32 v54, vcc, s95, v66
	v_fmac_f32_e32 v97, v56, v0
	s_nop 0
	v_addc_co_u32_e32 v55, vcc, 0, v67, vcc
	v_add_co_u32_e32 v56, vcc, s31, v66
	v_fmac_f32_e32 v98, v57, v0
	s_nop 0
	v_addc_co_u32_e32 v57, vcc, 0, v67, vcc
	s_waitcnt vmcnt(9)
	v_fmac_f32_e32 v100, v58, v0
	v_add_co_u32_e32 v58, vcc, s36, v66
	s_waitcnt vmcnt(8)
	v_fmac_f32_e32 v101, v59, v0
	v_addc_co_u32_e32 v59, vcc, 0, v67, vcc
	s_waitcnt vmcnt(7)
	v_fmac_f32_e32 v102, v60, v0
	v_add_co_u32_e32 v60, vcc, s37, v66
	s_waitcnt vmcnt(6)
	v_fmac_f32_e32 v103, v61, v0
	v_addc_co_u32_e32 v61, vcc, 0, v67, vcc
	s_waitcnt vmcnt(5)
	v_fmac_f32_e32 v104, v62, v0
	v_add_co_u32_e32 v62, vcc, s39, v66
	s_waitcnt vmcnt(4)
	v_fmac_f32_e32 v105, v63, v0
	s_waitcnt vmcnt(3)
	v_fmac_f32_e32 v106, v64, v0
	v_addc_co_u32_e32 v63, vcc, 0, v67, vcc
	s_waitcnt vmcnt(2)
	v_fmac_f32_e32 v107, v65, v0
	global_store_dword v[50:51], v94, off nt sc1
	global_store_dword v[52:53], v99, off nt sc1
	global_store_dword v[92:93], v95, off offset:-4096 nt sc1
	global_store_dword v[92:93], v96, off nt sc1
	global_store_dword v[54:55], v97, off offset:-4096 nt sc1
	global_store_dword v[54:55], v98, off nt sc1
	global_store_dword v[56:57], v100, off offset:-4096 nt sc1
	global_store_dword v[56:57], v101, off nt sc1
	global_store_dword v[58:59], v102, off offset:-4096 nt sc1
	global_store_dword v[58:59], v103, off nt sc1
	global_store_dword v[60:61], v104, off offset:-4096 nt sc1
	global_store_dword v[60:61], v105, off nt sc1
	global_store_dword v[62:63], v106, off offset:-4096 nt sc1
	global_store_dword v[62:63], v107, off nt sc1
	global_load_dword v0, v[114:115], off
	global_load_dword v94, v[68:69], off offset:128 nt
	v_add_co_u32_e32 v64, vcc, s0, v68
	global_load_dword v86, v[86:87], off offset:128 nt
	s_nop 0
	global_load_dword v87, v[70:71], off offset:128 nt
	global_load_dword v95, v[72:73], off offset:128 nt
	s_nop 0
	global_load_dword v88, v[88:89], off offset:128 nt
	v_addc_co_u32_e32 v65, vcc, 0, v69, vcc
	v_add_co_u32_e32 v70, vcc, s72, v68
	global_load_dword v89, v[74:75], off offset:128 nt
	global_load_dword v96, v[76:77], off offset:128 nt
	s_nop 0
	global_load_dword v90, v[90:91], off offset:128 nt
	s_nop 0
	global_load_dword v91, v[64:65], off offset:128 nt
	v_addc_co_u32_e32 v71, vcc, 0, v69, vcc
	v_add_co_u32_e32 v64, vcc, s1, v68
	s_waitcnt vmcnt(8)
	v_fmac_f32_e32 v94, v34, v0
	v_addc_co_u32_e32 v65, vcc, 0, v69, vcc
	global_load_dword v97, v[78:79], off offset:128 nt
	s_nop 0
	global_load_dword v80, v[80:81], off offset:128 nt
	s_nop 0
	global_load_dword v81, v[70:71], off offset:128 nt
	global_load_dword v98, v[64:65], off offset:128 nt
	v_add_co_u32_e32 v64, vcc, s38, v68
	v_or_b32_e32 v34, 0x60, v138
	s_nop 0
	v_addc_co_u32_e32 v65, vcc, 0, v69, vcc
	global_load_dword v82, v[82:83], off offset:128 nt
	s_nop 0
	global_load_dword v83, v[84:85], off offset:128 nt
	s_nop 0
	global_load_dword v84, v[64:65], off offset:128 nt
	v_add_co_u32_e32 v64, vcc, s28, v66
	s_waitcnt vmcnt(14)
	v_fmac_f32_e32 v86, v35, v0
	v_addc_co_u32_e32 v65, vcc, 0, v67, vcc
	v_add_co_u32_e32 v68, vcc, s94, v66
	v_ashrrev_i32_e32 v35, 31, v34
	s_nop 0
	v_addc_co_u32_e32 v69, vcc, 0, v67, vcc
	v_add_co_u32_e32 v70, vcc, s87, v66
	v_lshlrev_b64 v[34:35], 10, v[34:35]
	s_nop 0
	v_addc_co_u32_e32 v71, vcc, 0, v67, vcc
	v_add_co_u32_e32 v72, vcc, s0, v66
	v_lshl_add_u64 v[34:35], v[34:35], 0, v[136:137]
	s_nop 0
	v_addc_co_u32_e32 v73, vcc, 0, v67, vcc
	v_add_co_u32_e32 v74, vcc, s72, v66
	s_waitcnt vmcnt(13)
	v_fmac_f32_e32 v87, v36, v0
	v_addc_co_u32_e32 v75, vcc, 0, v67, vcc
	v_add_co_u32_e32 v76, vcc, s1, v66
	s_waitcnt vmcnt(12)
	v_fmac_f32_e32 v95, v37, v0
	v_addc_co_u32_e32 v77, vcc, 0, v67, vcc
	v_add_co_u32_e32 v78, vcc, s38, v66
	v_lshlrev_b64 v[36:37], 2, v[34:35]
	s_nop 0
	v_addc_co_u32_e32 v79, vcc, 0, v67, vcc
	v_lshl_add_u64 v[34:35], s[98:99], 0, v[36:37]
	s_waitcnt vmcnt(11)
	v_fmac_f32_e32 v88, v38, v0
	v_add_co_u32_e32 v38, vcc, s29, v34
	s_waitcnt vmcnt(10)
	v_fmac_f32_e32 v89, v39, v0
	v_addc_co_u32_e32 v39, vcc, 0, v35, vcc
	s_waitcnt vmcnt(8)
	v_fmac_f32_e32 v90, v40, v0
	v_fmac_f32_e32 v96, v41, v0
	s_waitcnt vmcnt(7)
	v_fmac_f32_e32 v91, v42, v0
	v_add_co_u32_e32 v40, vcc, s73, v34
	global_store_dword v[66:67], v94, off offset:128 nt sc1
	global_store_dword v[64:65], v86, off offset:128 nt sc1
	global_store_dword v[50:51], v87, off offset:128 nt sc1
	global_store_dword v[52:53], v95, off offset:128 nt sc1
	global_store_dword v[68:69], v88, off offset:128 nt sc1
	global_store_dword v[92:93], v89, off offset:128 nt sc1
	global_store_dword v[70:71], v90, off offset:128 nt sc1
	global_store_dword v[54:55], v96, off offset:128 nt sc1
	global_store_dword v[72:73], v91, off offset:128 nt sc1
	v_addc_co_u32_e32 v41, vcc, 0, v35, vcc
	v_add_co_u32_e32 v42, vcc, s75, v34
	v_lshl_add_u64 v[36:37], s[56:57], 0, v[36:37]
	s_waitcnt vmcnt(15)
	v_fmac_f32_e32 v97, v43, v0
	s_waitcnt vmcnt(14)
	v_fmac_f32_e32 v80, v45, v0
	s_waitcnt vmcnt(13)
	v_fmac_f32_e32 v81, v44, v0
	s_waitcnt vmcnt(12)
	v_fmac_f32_e32 v98, v46, v0
	global_store_dword v[56:57], v97, off offset:128 nt sc1
	global_store_dword v[74:75], v81, off offset:128 nt sc1
	global_store_dword v[58:59], v80, off offset:128 nt sc1
	s_waitcnt vmcnt(14)
	v_fmac_f32_e32 v82, v47, v0
	s_waitcnt vmcnt(13)
	v_fmac_f32_e32 v83, v49, v0
	s_waitcnt vmcnt(12)
	v_fmac_f32_e32 v84, v48, v0
	global_store_dword v[76:77], v98, off offset:128 nt sc1
	global_store_dword v[60:61], v82, off offset:128 nt sc1
	global_store_dword v[78:79], v84, off offset:128 nt sc1
	global_store_dword v[62:63], v83, off offset:128 nt sc1
	global_load_dword v0, v[140:141], off
	s_nop 0
	global_load_dword v60, v[34:35], off nt
	global_load_dword v61, v[38:39], off offset:-4096 nt
	v_addc_co_u32_e32 v43, vcc, 0, v35, vcc
	v_add_co_u32_e32 v44, vcc, s95, v34
	s_waitcnt vmcnt(1)
	v_fmac_f32_e32 v60, v18, v0
	v_addc_co_u32_e32 v45, vcc, 0, v35, vcc
	global_load_dword v62, v[38:39], off nt
	global_load_dword v63, v[42:43], off offset:-4096 nt
	global_load_dword v64, v[42:43], off nt
	global_load_dword v65, v[44:45], off offset:-4096 nt
	global_load_dword v66, v[44:45], off nt
	global_load_dword v67, v[40:41], off nt
	v_add_co_u32_e32 v46, vcc, s31, v34
	s_waitcnt vmcnt(6)
	v_fmac_f32_e32 v61, v19, v0
	v_addc_co_u32_e32 v47, vcc, 0, v35, vcc
	v_add_co_u32_e32 v48, vcc, s36, v34
	global_load_dword v68, v[46:47], off offset:-4096 nt
	global_load_dword v69, v[46:47], off nt
	v_addc_co_u32_e32 v49, vcc, 0, v35, vcc
	v_add_co_u32_e32 v50, vcc, s37, v34
	global_load_dword v70, v[48:49], off offset:-4096 nt
	global_load_dword v71, v[48:49], off nt
	v_addc_co_u32_e32 v51, vcc, 0, v35, vcc
	v_add_co_u32_e32 v52, vcc, s39, v34
	global_load_dword v72, v[50:51], off offset:-4096 nt
	global_load_dword v73, v[50:51], off nt
	v_addc_co_u32_e32 v53, vcc, 0, v35, vcc
	global_load_dword v74, v[52:53], off offset:-4096 nt
	global_load_dword v75, v[52:53], off nt
	v_add_co_u32_e32 v54, vcc, s28, v34
	global_store_dword v[36:37], v60, off nt sc1
	s_nop 0
	v_addc_co_u32_e32 v55, vcc, 0, v35, vcc
	v_add_co_u32_e32 v56, vcc, s94, v34
	s_waitcnt vmcnt(14)
	v_fmac_f32_e32 v62, v20, v0
	v_addc_co_u32_e32 v57, vcc, 0, v35, vcc
	v_add_co_u32_e32 v58, vcc, s87, v34
	s_waitcnt vmcnt(9)
	v_fmac_f32_e32 v67, v21, v0
	v_addc_co_u32_e32 v59, vcc, 0, v35, vcc
	v_add_co_u32_e32 v18, vcc, s29, v36
	v_fmac_f32_e32 v63, v22, v0
	s_nop 0
	v_addc_co_u32_e32 v19, vcc, 0, v37, vcc
	v_add_co_u32_e32 v20, vcc, s73, v36
	global_store_dword v[18:19], v61, off offset:-4096 nt sc1
	s_nop 0
	v_addc_co_u32_e32 v21, vcc, 0, v37, vcc
	v_add_co_u32_e32 v60, vcc, s75, v36
	v_fmac_f32_e32 v64, v23, v0
	s_nop 0
	v_addc_co_u32_e32 v61, vcc, 0, v37, vcc
	v_add_co_u32_e32 v22, vcc, s95, v36
	v_fmac_f32_e32 v65, v24, v0
	s_nop 0
	v_addc_co_u32_e32 v23, vcc, 0, v37, vcc
	v_add_co_u32_e32 v24, vcc, s31, v36
	v_fmac_f32_e32 v66, v25, v0
	s_nop 0
	v_addc_co_u32_e32 v25, vcc, 0, v37, vcc
	s_waitcnt vmcnt(9)
	v_fmac_f32_e32 v68, v26, v0
	v_add_co_u32_e32 v26, vcc, s36, v36
	s_waitcnt vmcnt(8)
	v_fmac_f32_e32 v69, v27, v0
	v_addc_co_u32_e32 v27, vcc, 0, v37, vcc
	s_waitcnt vmcnt(7)
	v_fmac_f32_e32 v70, v28, v0
	v_add_co_u32_e32 v28, vcc, s37, v36
	s_waitcnt vmcnt(6)
	v_fmac_f32_e32 v71, v29, v0
	v_addc_co_u32_e32 v29, vcc, 0, v37, vcc
	s_waitcnt vmcnt(5)
	v_fmac_f32_e32 v72, v30, v0
	v_add_co_u32_e32 v30, vcc, s39, v36
	s_waitcnt vmcnt(4)
	v_fmac_f32_e32 v73, v31, v0
	v_addc_co_u32_e32 v31, vcc, 0, v37, vcc
	s_waitcnt vmcnt(3)
	v_fmac_f32_e32 v74, v32, v0
	s_waitcnt vmcnt(2)
	v_fmac_f32_e32 v75, v33, v0
	v_add_co_u32_e32 v32, vcc, s0, v34
	global_store_dword v[18:19], v62, off nt sc1
	global_store_dword v[20:21], v67, off nt sc1
	global_store_dword v[60:61], v63, off offset:-4096 nt sc1
	global_store_dword v[60:61], v64, off nt sc1
	global_store_dword v[22:23], v65, off offset:-4096 nt sc1
	global_store_dword v[22:23], v66, off nt sc1
	global_store_dword v[24:25], v68, off offset:-4096 nt sc1
	global_store_dword v[24:25], v69, off nt sc1
	global_store_dword v[26:27], v70, off offset:-4096 nt sc1
	global_store_dword v[26:27], v71, off nt sc1
	global_store_dword v[28:29], v72, off offset:-4096 nt sc1
	global_store_dword v[28:29], v73, off nt sc1
	global_store_dword v[30:31], v74, off offset:-4096 nt sc1
	global_store_dword v[30:31], v75, off nt sc1
	v_addc_co_u32_e32 v33, vcc, 0, v35, vcc
	global_load_dword v0, v[114:115], off
	global_load_dword v62, v[34:35], off offset:128 nt
	s_nop 0
	global_load_dword v54, v[54:55], off offset:128 nt
	s_nop 0
	global_load_dword v55, v[38:39], off offset:128 nt
	global_load_dword v63, v[40:41], off offset:128 nt
	s_nop 0
	global_load_dword v56, v[56:57], off offset:128 nt
	v_add_co_u32_e32 v38, vcc, s72, v34
	global_load_dword v57, v[42:43], off offset:128 nt
	global_load_dword v64, v[44:45], off offset:128 nt
	s_nop 0
	global_load_dword v58, v[58:59], off offset:128 nt
	s_nop 0
	global_load_dword v59, v[32:33], off offset:128 nt
	v_addc_co_u32_e32 v39, vcc, 0, v35, vcc
	v_add_co_u32_e32 v32, vcc, s1, v34
	s_waitcnt vmcnt(7)
	v_fmac_f32_e32 v54, v3, v0
	v_addc_co_u32_e32 v33, vcc, 0, v35, vcc
	global_load_dword v65, v[46:47], off offset:128 nt
	s_nop 0
	global_load_dword v48, v[48:49], off offset:128 nt
	s_nop 0
	global_load_dword v49, v[38:39], off offset:128 nt
	global_load_dword v66, v[32:33], off offset:128 nt
	v_add_co_u32_e32 v32, vcc, s38, v34
	v_fmac_f32_e32 v62, v2, v0
	s_nop 0
	v_addc_co_u32_e32 v33, vcc, 0, v35, vcc
	global_load_dword v50, v[50:51], off offset:128 nt
	s_nop 0
	global_load_dword v51, v[52:53], off offset:128 nt
	s_nop 0
	global_load_dword v52, v[32:33], off offset:128 nt
	v_add_co_u32_e32 v32, vcc, s28, v36
	s_waitcnt vmcnt(13)
	v_fmac_f32_e32 v55, v4, v0
	v_addc_co_u32_e32 v33, vcc, 0, v37, vcc
	v_add_co_u32_e32 v34, vcc, s94, v36
	s_waitcnt vmcnt(12)
	v_fmac_f32_e32 v63, v5, v0
	v_addc_co_u32_e32 v35, vcc, 0, v37, vcc
	v_add_co_u32_e32 v38, vcc, s87, v36
	s_waitcnt vmcnt(11)
	v_fmac_f32_e32 v56, v6, v0
	v_addc_co_u32_e32 v39, vcc, 0, v37, vcc
	v_add_co_u32_e32 v40, vcc, s0, v36
	s_waitcnt vmcnt(10)
	v_fmac_f32_e32 v57, v7, v0
	v_addc_co_u32_e32 v41, vcc, 0, v37, vcc
	v_add_co_u32_e32 v42, vcc, s72, v36
	s_waitcnt vmcnt(8)
	v_fmac_f32_e32 v58, v8, v0
	v_addc_co_u32_e32 v43, vcc, 0, v37, vcc
	v_add_co_u32_e32 v44, vcc, s1, v36
	v_fmac_f32_e32 v64, v9, v0
	s_nop 0
	v_addc_co_u32_e32 v45, vcc, 0, v37, vcc
	v_add_co_u32_e32 v46, vcc, s38, v36
	s_waitcnt vmcnt(7)
	v_fmac_f32_e32 v59, v10, v0
	v_addc_co_u32_e32 v47, vcc, 0, v37, vcc
	global_store_dword v[36:37], v62, off offset:128 nt sc1
	global_store_dword v[32:33], v54, off offset:128 nt sc1
	global_store_dword v[18:19], v55, off offset:128 nt sc1
	global_store_dword v[20:21], v63, off offset:128 nt sc1
	global_store_dword v[34:35], v56, off offset:128 nt sc1
	global_store_dword v[60:61], v57, off offset:128 nt sc1
	global_store_dword v[38:39], v58, off offset:128 nt sc1
	global_store_dword v[22:23], v64, off offset:128 nt sc1
	global_store_dword v[40:41], v59, off offset:128 nt sc1
	s_waitcnt vmcnt(15)
	v_fmac_f32_e32 v65, v11, v0
	s_waitcnt vmcnt(14)
	v_fmac_f32_e32 v48, v13, v0
	s_waitcnt vmcnt(13)
	v_fmac_f32_e32 v49, v12, v0
	s_waitcnt vmcnt(12)
	v_fmac_f32_e32 v66, v14, v0
	global_store_dword v[24:25], v65, off offset:128 nt sc1
	global_store_dword v[42:43], v49, off offset:128 nt sc1
	global_store_dword v[26:27], v48, off offset:128 nt sc1
	s_waitcnt vmcnt(14)
	v_fmac_f32_e32 v50, v15, v0
	s_waitcnt vmcnt(13)
	v_fmac_f32_e32 v51, v17, v0
	s_waitcnt vmcnt(12)
	v_fmac_f32_e32 v52, v16, v0
	global_store_dword v[44:45], v66, off offset:128 nt sc1
	global_store_dword v[28:29], v50, off offset:128 nt sc1
	global_store_dword v[46:47], v52, off offset:128 nt sc1
	global_store_dword v[30:31], v51, off offset:128 nt sc1
	s_cbranch_scc0 .LBB0_52
